# baseline (speedup 1.0000x reference)
; #define tidx() tidx_(wv_)
; __device__ __forceinline__ float* outp(unsigned char* ws) { return (float*)inp(ws, 33); }
; __device__ __forceinline__ void final_norm(unsigned char* ws, int wv_) {
;   const float* ss = (const float*)(ws + OFF_SS) + 8 * T_;
;   const float* g = inp(ws, 32);
;   float* x = outp(ws);
;   int wave = tidx() >> 6, lane = tidx() & 63;
;   for (int row = bidx() * 8 + wave; row < T_; row += gridDim.x * 8) {
;     float s = rsqrtf(ss[row] * (1.f / D_) + 1e-6f);
;     for (int i = 0; i < 8; ++i) {
;       int col = (i * 64 + lane) * 4;
;       float4 v = *(float4*)(x + (size_t)row * D_ + col);
;       float4 gg = *(const float4*)(g + col);
;       v.x *= s * gg.x; v.y *= s * gg.y; v.z *= s * gg.z; v.w *= s * gg.w;
;       *(float4*)(x + (size_t)row * D_ + col) = v;
;     }
;   }
; }
.LBB0_1551:
	s_waitcnt vmcnt(0)
	v_mbcnt_lo_u32_b32 v0, -1, 0
	v_mbcnt_hi_u32_b32 v0, -1, v0
	v_readlane_b32 s2, v251, 14
	v_or_b32_e32 v0, s63, v0
	v_ashrrev_i32_e32 v0, 6, v0
	v_add_u32_e32 v0, s2, v0
	s_movk_i32 s2, 0x2000
	v_cmp_gt_i32_e32 vcc, s2, v0
	v_mbcnt_lo_u32_b32 v1, -1, 0
	v_mbcnt_hi_u32_b32 v1, -1, v1
	s_and_saveexec_b64 s[2:3], vcc
	s_cbranch_execz .LBB0_1554
	s_load_dwordx4 s[4:7], s[0:1], 0x100
	v_lshlrev_b32_e32 v2, 4, v1
	v_mov_b32_e32 v3, 0
	v_readfirstlane_b32 s17, v0
	s_add_u32 s10, s78, 0x2b180000
	s_addc_u32 s11, s79, 0
	s_lshl_b32 s8, s39, 3
	v_mov_b32_e32 v22, 0x358637bd
	s_mov_b32 s16, 0x800000
	s_waitcnt lgkmcnt(0)
	s_add_u32 s12, s4, 0x1000
	s_addc_u32 s13, s5, 0
	global_load_dwordx4 v[48:51], v2, s[4:5]
	global_load_dwordx4 v[52:55], v2, s[4:5] offset:1024
	global_load_dwordx4 v[56:59], v2, s[4:5] offset:2048
	global_load_dwordx4 v[60:63], v2, s[4:5] offset:3072
	global_load_dwordx4 v[64:67], v2, s[12:13]
	global_load_dwordx4 v[68:71], v2, s[12:13] offset:1024
	global_load_dwordx4 v[72:75], v2, s[12:13] offset:2048
	global_load_dwordx4 v[76:79], v2, s[12:13] offset:3072
.Lfn_loop:
	s_lshl_b32 s18, s17, 2
	v_mov_b32_e32 v4, s18
	global_load_dword v6, v4, s[10:11]
	s_lshr_b32 s19, s17, 19
	s_lshl_b32 s18, s17, 13
	s_add_u32 s18, s6, s18
	s_addc_u32 s19, s7, s19
	s_add_u32 s20, s18, 0x1000
	s_addc_u32 s21, s19, 0
	global_load_dwordx4 v[80:83], v2, s[18:19]
	global_load_dwordx4 v[84:87], v2, s[18:19] offset:1024
	global_load_dwordx4 v[88:91], v2, s[18:19] offset:2048
	global_load_dwordx4 v[92:95], v2, s[18:19] offset:3072
	global_load_dwordx4 v[96:99], v2, s[20:21]
	global_load_dwordx4 v[100:103], v2, s[20:21] offset:1024
	global_load_dwordx4 v[104:107], v2, s[20:21] offset:2048
	global_load_dwordx4 v[108:111], v2, s[20:21] offset:3072
	s_waitcnt vmcnt(8)
	v_fmamk_f32 v7, v6, 0x3a000000, v22
	v_mul_f32_e32 v8, 0x4b800000, v7
	v_cmp_gt_f32_e32 vcc, s16, v7
	s_nop 1
	v_cndmask_b32_e32 v7, v7, v8, vcc
	v_rsq_f32_e32 v7, v7
	s_nop 0
	v_mul_f32_e32 v8, 0x45800000, v7
	v_cndmask_b32_e32 v40, v7, v8, vcc
	s_waitcnt vmcnt(7)
	v_pk_mul_f32 v[112:113], v[48:49], v[40:41] op_sel_hi:[1,0]
	v_pk_mul_f32 v[114:115], v[50:51], v[40:41] op_sel_hi:[1,0]
	v_pk_mul_f32 v[80:81], v[80:81], v[112:113]
	v_pk_mul_f32 v[82:83], v[82:83], v[114:115]
	s_waitcnt vmcnt(6)
	v_pk_mul_f32 v[112:113], v[52:53], v[40:41] op_sel_hi:[1,0]
	v_pk_mul_f32 v[114:115], v[54:55], v[40:41] op_sel_hi:[1,0]
	v_pk_mul_f32 v[84:85], v[84:85], v[112:113]
	v_pk_mul_f32 v[86:87], v[86:87], v[114:115]
	s_waitcnt vmcnt(5)
	v_pk_mul_f32 v[112:113], v[56:57], v[40:41] op_sel_hi:[1,0]
	v_pk_mul_f32 v[114:115], v[58:59], v[40:41] op_sel_hi:[1,0]
	v_pk_mul_f32 v[88:89], v[88:89], v[112:113]
	v_pk_mul_f32 v[90:91], v[90:91], v[114:115]
	s_waitcnt vmcnt(4)
	v_pk_mul_f32 v[112:113], v[60:61], v[40:41] op_sel_hi:[1,0]
	v_pk_mul_f32 v[114:115], v[62:63], v[40:41] op_sel_hi:[1,0]
	v_pk_mul_f32 v[92:93], v[92:93], v[112:113]
	v_pk_mul_f32 v[94:95], v[94:95], v[114:115]
	s_waitcnt vmcnt(3)
	v_pk_mul_f32 v[112:113], v[64:65], v[40:41] op_sel_hi:[1,0]
	v_pk_mul_f32 v[114:115], v[66:67], v[40:41] op_sel_hi:[1,0]
	v_pk_mul_f32 v[96:97], v[96:97], v[112:113]
	v_pk_mul_f32 v[98:99], v[98:99], v[114:115]
	s_waitcnt vmcnt(2)
	v_pk_mul_f32 v[112:113], v[68:69], v[40:41] op_sel_hi:[1,0]
	v_pk_mul_f32 v[114:115], v[70:71], v[40:41] op_sel_hi:[1,0]
	v_pk_mul_f32 v[100:101], v[100:101], v[112:113]
	v_pk_mul_f32 v[102:103], v[102:103], v[114:115]
	s_waitcnt vmcnt(1)
	v_pk_mul_f32 v[112:113], v[72:73], v[40:41] op_sel_hi:[1,0]
	v_pk_mul_f32 v[114:115], v[74:75], v[40:41] op_sel_hi:[1,0]
	v_pk_mul_f32 v[104:105], v[104:105], v[112:113]
	v_pk_mul_f32 v[106:107], v[106:107], v[114:115]
	s_waitcnt vmcnt(0)
	v_pk_mul_f32 v[112:113], v[76:77], v[40:41] op_sel_hi:[1,0]
	v_pk_mul_f32 v[114:115], v[78:79], v[40:41] op_sel_hi:[1,0]
	v_pk_mul_f32 v[108:109], v[108:109], v[112:113]
	v_pk_mul_f32 v[110:111], v[110:111], v[114:115]
	global_store_dwordx4 v2, v[80:83], s[18:19]
	global_store_dwordx4 v2, v[84:87], s[18:19] offset:1024
	global_store_dwordx4 v2, v[88:91], s[18:19] offset:2048
	global_store_dwordx4 v2, v[92:95], s[18:19] offset:3072
	global_store_dwordx4 v2, v[96:99], s[20:21]
	global_store_dwordx4 v2, v[100:103], s[20:21] offset:1024
	global_store_dwordx4 v2, v[104:107], s[20:21] offset:2048
	global_store_dwordx4 v2, v[108:111], s[20:21] offset:3072
	s_add_i32 s17, s17, s8
	s_cmpk_lt_i32 s17, 0x2000
	s_cbranch_scc1 .Lfn_loop
